# MLP-down (X2) epilogue: residual loads of row groups 1-6 issued up front into dead fragment registers; counted waits instead of vmcnt(0) after every store
# baseline (speedup 1.0000x reference)
; __device__ __forceinline__ unsigned cvt_pk_bf16(float lo, float hi) { const f32x2c_t v = {lo, hi}; const bf16x2c_t b = __builtin_convertvector(v, bf16x2c_t); return __builtin_bit_cast(unsigned, b); }
; __device__ __forceinline__ float bf_lo(unsigned w) { return __uint_as_float(w << 16); }
; __device__ __forceinline__ float bf_hi(unsigned w) { return __uint_as_float(w & 0xffff0000u); }
;     __device__ __forceinline__ void operator()(const f32x4 (&acc)[2][2][4][2], const Unit& u, int wr, int wc, int fr, int fq) const {
;     ...
;             for (int m = 0; m < 4; ++m) { const size_t row = (size_t)(row0 + ai * HALF + m * 16); float ss = 0.f;
; #pragma unroll
;                 for (int bj = 0; bj < 2; ++bj) { const size_t off = row * DM + col0 + bj * HALF;
;                     const u32x4 pw = *(const u32x4*)(XN + off);
;                     f32x4 v0 = acc[ai][bj][m][0] + (f32x4){bf_lo(pw.x), bf_hi(pw.x), bf_lo(pw.y), bf_hi(pw.y)}, v1 = acc[ai][bj][m][1] + (f32x4){bf_lo(pw.z), bf_hi(pw.z), bf_lo(pw.w), bf_hi(pw.w)};
;                     u32x4 w; w.x = cvt_pk_bf16(v0[0], v0[1]); w.y = cvt_pk_bf16(v0[2], v0[3]); w.z = cvt_pk_bf16(v1[0], v1[1]); w.w = cvt_pk_bf16(v1[2], v1[3]);
;                     *(u32x4*)(X2 + off) = w;
;                     v0 = (f32x4){bf_lo(w.x), bf_hi(w.x), bf_lo(w.y), bf_hi(w.y)}; v1 = (f32x4){bf_lo(w.z), bf_hi(w.z), bf_lo(w.w), bf_hi(w.w)};
;                     ss += (v0[0] * v0[0] + v0[1] * v0[1]) + (v0[2] * v0[2] + v0[3] * v0[3]) + (v1[0] * v1[0] + v1[1] * v1[1]) + (v1[2] * v1[2] + v1[3] * v1[3]); }
;                 ss += __shfl_xor(ss, 16); ss += __shfl_xor(ss, 32);
;                 if (fq == 0) SS[row * 32 + u.pn * 4 + wc] = ss; }
.LBB0_39:
	v_xor_b32_e32 v159, 16, v192
	v_add_u32_e32 v160, 64, v193
	v_cmp_lt_i32_e32 vcc, v159, v160
	v_lshl_add_u32 v158, s54, 8, v1
	v_lshl_or_b32 v156, s28, 8, v162
	v_cndmask_b32_e32 v159, v192, v159, vcc
	v_lshlrev_b32_e32 v164, 2, v159
	v_xor_b32_e32 v159, 32, v192
	v_cmp_lt_i32_e32 vcc, v159, v160
	v_ashrrev_i32_e32 v157, 31, v156
	s_lshl_b32 s58, s28, 2
	v_cndmask_b32_e32 v159, v192, v159, vcc
	v_lshlrev_b32_e32 v165, 2, v159
	v_ashrrev_i32_e32 v159, 31, v158
	v_lshlrev_b64 v[160:161], 11, v[158:159]
	v_lshl_add_u64 v[160:161], v[160:161], 0, v[156:157]
	v_lshlrev_b64 v[160:161], 1, v[160:161]
	v_lshl_add_u64 v[166:167], s[70:71], 0, v[160:161]
	global_load_dwordx4 v[166:169], v[166:167], off
	s_ashr_i32 s59, s58, 31
	v_or_b32_e32 v204, 16, v158
	v_ashrrev_i32_e32 v205, 31, v204
	v_lshlrev_b64 v[206:207], 11, v[204:205]
	v_lshl_add_u64 v[206:207], v[206:207], 0, v[156:157]
	v_lshlrev_b64 v[206:207], 1, v[206:207]
	v_lshl_add_u64 v[206:207], s[70:71], 0, v[206:207]
	global_load_dwordx4 v[208:211], v[206:207], off offset:256
	global_load_dwordx4 v[204:207], v[206:207], off
	v_or_b32_e32 v212, 32, v158
	v_ashrrev_i32_e32 v213, 31, v212
	v_lshlrev_b64 v[214:215], 11, v[212:213]
	v_lshl_add_u64 v[214:215], v[214:215], 0, v[156:157]
	v_lshlrev_b64 v[214:215], 1, v[214:215]
	v_lshl_add_u64 v[214:215], s[70:71], 0, v[214:215]
	global_load_dwordx4 v[216:219], v[214:215], off offset:256
	global_load_dwordx4 v[212:215], v[214:215], off
	v_or_b32_e32 v220, 48, v158
	v_ashrrev_i32_e32 v221, 31, v220
	v_lshlrev_b64 v[222:223], 11, v[220:221]
	v_lshl_add_u64 v[222:223], v[222:223], 0, v[156:157]
	v_lshlrev_b64 v[222:223], 1, v[222:223]
	v_lshl_add_u64 v[222:223], s[70:71], 0, v[222:223]
	global_load_dwordx4 v[224:227], v[222:223], off offset:256
	global_load_dwordx4 v[220:223], v[222:223], off
	v_add_u32_e32 v228, 0x80, v158
	v_ashrrev_i32_e32 v229, 31, v228
	v_lshlrev_b64 v[230:231], 11, v[228:229]
	v_lshl_add_u64 v[230:231], v[230:231], 0, v[156:157]
	v_lshlrev_b64 v[230:231], 1, v[230:231]
	v_lshl_add_u64 v[230:231], s[70:71], 0, v[230:231]
	global_load_dwordx4 v[232:235], v[230:231], off offset:256
	global_load_dwordx4 v[228:231], v[230:231], off
	v_add_u32_e32 v236, 0x90, v158
	v_ashrrev_i32_e32 v237, 31, v236
	v_lshlrev_b64 v[238:239], 11, v[236:237]
	v_lshl_add_u64 v[238:239], v[238:239], 0, v[156:157]
	v_lshlrev_b64 v[238:239], 1, v[238:239]
	v_lshl_add_u64 v[238:239], s[70:71], 0, v[238:239]
	global_load_dwordx4 v[240:243], v[238:239], off offset:256
	global_load_dwordx4 v[236:239], v[238:239], off
	v_add_u32_e32 v176, 0xa0, v158
	v_ashrrev_i32_e32 v177, 31, v176
	v_lshlrev_b64 v[178:179], 11, v[176:177]
	v_lshl_add_u64 v[178:179], v[178:179], 0, v[156:157]
	v_lshlrev_b64 v[178:179], 1, v[178:179]
	v_lshl_add_u64 v[178:179], s[70:71], 0, v[178:179]
	global_load_dwordx4 v[180:183], v[178:179], off offset:256
	global_load_dwordx4 v[176:179], v[178:179], off
	s_waitcnt vmcnt(12)
	v_lshlrev_b32_e32 v170, 16, v166
	v_and_b32_e32 v171, 0xffff0000, v166
	v_lshlrev_b32_e32 v166, 16, v167
	v_and_b32_e32 v167, 0xffff0000, v167
	v_pk_add_f32 v[128:129], v[128:129], v[166:167]
	v_lshlrev_b32_e32 v166, 16, v168
	v_and_b32_e32 v167, 0xffff0000, v168
	v_lshlrev_b32_e32 v168, 16, v169
	v_and_b32_e32 v169, 0xffff0000, v169
	v_pk_add_f32 v[126:127], v[126:127], v[170:171]
	v_pk_add_f32 v[168:169], v[124:125], v[168:169]
	v_pk_add_f32 v[124:125], v[122:123], v[166:167]
	v_cvt_pk_bf16_f32 v122, v126, v127
	v_cvt_pk_bf16_f32 v123, v128, v129
	v_cvt_pk_bf16_f32 v124, v124, v125
	v_cvt_pk_bf16_f32 v125, v168, v169
	v_lshl_add_u64 v[126:127], s[6:7], 0, v[160:161]
	global_store_dwordx4 v[126:127], v[122:125], off
	v_lshlrev_b32_e32 v126, 16, v122
	v_lshlrev_b32_e32 v127, 16, v123
	v_and_b32_e32 v122, 0xffff0000, v122
	v_and_b32_e32 v123, 0xffff0000, v123
	v_mul_f32_e32 v122, v122, v122
	v_mul_f32_e32 v123, v123, v123
	v_lshlrev_b32_e32 v128, 16, v124
	v_and_b32_e32 v124, 0xffff0000, v124
	v_fmac_f32_e32 v122, v126, v126
	v_fmac_f32_e32 v123, v127, v127
	v_add_f32_e32 v122, v122, v123
	v_mul_f32_e32 v123, v124, v124
	v_lshlrev_b32_e32 v129, 16, v125
	v_and_b32_e32 v125, 0xffff0000, v125
	v_fmac_f32_e32 v123, v128, v128
	v_add_f32_e32 v122, v123, v122
	v_mul_f32_e32 v123, v125, v125
	v_fmac_f32_e32 v123, v129, v129
	v_or_b32_e32 v160, 0x100, v160
	v_add_f32_e32 v128, v123, v122
	v_lshl_add_u64 v[122:123], s[70:71], 0, v[160:161]
	global_load_dwordx4 v[122:125], v[122:123], off
	s_waitcnt vmcnt(0)
	v_lshlrev_b32_e32 v126, 16, v122
	v_and_b32_e32 v127, 0xffff0000, v122
	v_lshlrev_b32_e32 v122, 16, v123
	v_and_b32_e32 v123, 0xffff0000, v123
	v_pk_add_f32 v[120:121], v[120:121], v[122:123]
	v_lshlrev_b32_e32 v122, 16, v124
	v_and_b32_e32 v123, 0xffff0000, v124
	v_lshlrev_b32_e32 v124, 16, v125
	v_and_b32_e32 v125, 0xffff0000, v125
	v_pk_add_f32 v[118:119], v[118:119], v[126:127]
	v_pk_add_f32 v[124:125], v[116:117], v[124:125]
	v_pk_add_f32 v[116:117], v[114:115], v[122:123]
	v_cvt_pk_bf16_f32 v114, v118, v119
	v_cvt_pk_bf16_f32 v115, v120, v121
	v_cvt_pk_bf16_f32 v116, v116, v117
	v_cvt_pk_bf16_f32 v117, v124, v125
	v_lshl_add_u64 v[118:119], s[6:7], 0, v[160:161]
	global_store_dwordx4 v[118:119], v[114:117], off
	v_lshlrev_b32_e32 v118, 16, v114
	v_lshlrev_b32_e32 v119, 16, v115
	v_and_b32_e32 v114, 0xffff0000, v114
	v_and_b32_e32 v115, 0xffff0000, v115
	v_mul_f32_e32 v114, v114, v114
	v_mul_f32_e32 v115, v115, v115
	v_lshlrev_b32_e32 v120, 16, v116
	v_and_b32_e32 v116, 0xffff0000, v116
	v_fmac_f32_e32 v114, v118, v118
	v_fmac_f32_e32 v115, v119, v119
	v_add_f32_e32 v114, v114, v115
	v_mul_f32_e32 v115, v116, v116
	v_lshlrev_b32_e32 v121, 16, v117
	v_and_b32_e32 v117, 0xffff0000, v117
	v_fmac_f32_e32 v115, v120, v120
	v_add_f32_e32 v114, v115, v114
	v_mul_f32_e32 v115, v117, v117
	v_fmac_f32_e32 v115, v121, v121
	v_add_f32_e32 v114, v115, v114
	v_add_f32_e32 v114, v128, v114
	ds_bpermute_b32 v115, v164, v114
	s_waitcnt lgkmcnt(0)
	v_add_f32_e32 v114, v114, v115
	ds_bpermute_b32 v115, v165, v114
	s_and_saveexec_b64 s[18:19], s[40:41]
	s_cbranch_execz .LBB0_41
	v_lshlrev_b64 v[116:117], 7, v[158:159]
	v_lshl_add_u64 v[116:117], s[10:11], 0, v[116:117]
	v_lshl_add_u64 v[116:117], s[58:59], 2, v[116:117]
	s_lshl_b32 s54, s0, 2
	v_lshl_add_u64 v[116:117], v[116:117], 0, s[54:55]
	s_waitcnt lgkmcnt(0)
	v_add_f32_e32 v114, v114, v115
	global_store_dword v[116:117], v114, off
; __device__ __forceinline__ unsigned cvt_pk_bf16(float lo, float hi) { const f32x2c_t v = {lo, hi}; const bf16x2c_t b = __builtin_convertvector(v, bf16x2c_t); return __builtin_bit_cast(unsigned, b); }
; __device__ __forceinline__ float bf_lo(unsigned w) { return __uint_as_float(w << 16); }
; __device__ __forceinline__ float bf_hi(unsigned w) { return __uint_as_float(w & 0xffff0000u); }
;     __device__ __forceinline__ void operator()(const f32x4 (&acc)[2][2][4][2], const Unit& u, int wr, int wc, int fr, int fq) const {
;     ...
;             for (int m = 0; m < 4; ++m) { const size_t row = (size_t)(row0 + ai * HALF + m * 16); float ss = 0.f;
; #pragma unroll
;                 for (int bj = 0; bj < 2; ++bj) { const size_t off = row * DM + col0 + bj * HALF;
;                     const u32x4 pw = *(const u32x4*)(XN + off);
;                     f32x4 v0 = acc[ai][bj][m][0] + (f32x4){bf_lo(pw.x), bf_hi(pw.x), bf_lo(pw.y), bf_hi(pw.y)}, v1 = acc[ai][bj][m][1] + (f32x4){bf_lo(pw.z), bf_hi(pw.z), bf_lo(pw.w), bf_hi(pw.w)};
;                     u32x4 w; w.x = cvt_pk_bf16(v0[0], v0[1]); w.y = cvt_pk_bf16(v0[2], v0[3]); w.z = cvt_pk_bf16(v1[0], v1[1]); w.w = cvt_pk_bf16(v1[2], v1[3]);
;                     *(u32x4*)(X2 + off) = w;
;                     v0 = (f32x4){bf_lo(w.x), bf_hi(w.x), bf_lo(w.y), bf_hi(w.y)}; v1 = (f32x4){bf_lo(w.z), bf_hi(w.z), bf_lo(w.w), bf_hi(w.w)};
;                     ss += (v0[0] * v0[0] + v0[1] * v0[1]) + (v0[2] * v0[2] + v0[3] * v0[3]) + (v1[0] * v1[0] + v1[1] * v1[1]) + (v1[2] * v1[2] + v1[3] * v1[3]); }
;                 ss += __shfl_xor(ss, 16); ss += __shfl_xor(ss, 32);
;                 if (fq == 0) SS[row * 32 + u.pn * 4 + wc] = ss; }
.LBB0_41:
	s_or_b64 exec, exec, s[18:19]
	v_or_b32_e32 v114, 16, v158
	s_waitcnt lgkmcnt(0)
	v_ashrrev_i32_e32 v115, 31, v114
	v_lshlrev_b64 v[116:117], 11, v[114:115]
	v_lshl_add_u64 v[116:117], v[116:117], 0, v[156:157]
	v_lshlrev_b64 v[116:117], 1, v[116:117]
	v_lshl_add_u64 v[118:119], s[70:71], 0, v[116:117]
	s_waitcnt vmcnt(12)
	v_mov_b32_e32 v118, v204
	v_mov_b32_e32 v119, v205
	v_mov_b32_e32 v120, v206
	v_mov_b32_e32 v121, v207
	v_lshlrev_b32_e32 v122, 16, v118
	v_and_b32_e32 v123, 0xffff0000, v118
	v_lshlrev_b32_e32 v118, 16, v119
	v_and_b32_e32 v119, 0xffff0000, v119
	v_pk_add_f32 v[112:113], v[112:113], v[118:119]
	v_lshlrev_b32_e32 v118, 16, v120
	v_and_b32_e32 v119, 0xffff0000, v120
	v_lshlrev_b32_e32 v120, 16, v121
	v_and_b32_e32 v121, 0xffff0000, v121
	v_pk_add_f32 v[110:111], v[110:111], v[122:123]
	v_pk_add_f32 v[120:121], v[108:109], v[120:121]
	v_pk_add_f32 v[108:109], v[106:107], v[118:119]
	v_cvt_pk_bf16_f32 v106, v110, v111
	v_cvt_pk_bf16_f32 v107, v112, v113
	v_cvt_pk_bf16_f32 v108, v108, v109
	v_cvt_pk_bf16_f32 v109, v120, v121
	v_lshl_add_u64 v[110:111], s[6:7], 0, v[116:117]
	global_store_dwordx4 v[110:111], v[106:109], off
	v_lshlrev_b32_e32 v110, 16, v106
	v_lshlrev_b32_e32 v111, 16, v107
	v_and_b32_e32 v106, 0xffff0000, v106
	v_and_b32_e32 v107, 0xffff0000, v107
	v_mul_f32_e32 v106, v106, v106
	v_mul_f32_e32 v107, v107, v107
	v_lshlrev_b32_e32 v112, 16, v108
	v_and_b32_e32 v108, 0xffff0000, v108
	v_fmac_f32_e32 v106, v110, v110
	v_fmac_f32_e32 v107, v111, v111
	v_add_f32_e32 v106, v106, v107
	v_mul_f32_e32 v107, v108, v108
	v_lshlrev_b32_e32 v113, 16, v109
	v_and_b32_e32 v109, 0xffff0000, v109
	v_fmac_f32_e32 v107, v112, v112
	v_add_f32_e32 v106, v107, v106
	v_mul_f32_e32 v107, v109, v109
	v_fmac_f32_e32 v107, v113, v113
	v_or_b32_e32 v116, 0x100, v116
	v_add_f32_e32 v112, v107, v106
	v_lshl_add_u64 v[106:107], s[70:71], 0, v[116:117]
	s_waitcnt vmcnt(14)
	v_mov_b32_e32 v106, v208
	v_mov_b32_e32 v107, v209
	v_mov_b32_e32 v108, v210
	v_mov_b32_e32 v109, v211
	v_lshlrev_b32_e32 v110, 16, v106
	v_and_b32_e32 v111, 0xffff0000, v106
	v_lshlrev_b32_e32 v106, 16, v107
	v_and_b32_e32 v107, 0xffff0000, v107
	v_pk_add_f32 v[104:105], v[104:105], v[106:107]
	v_lshlrev_b32_e32 v106, 16, v108
	v_and_b32_e32 v107, 0xffff0000, v108
	v_lshlrev_b32_e32 v108, 16, v109
	v_and_b32_e32 v109, 0xffff0000, v109
	v_pk_add_f32 v[102:103], v[102:103], v[110:111]
	v_pk_add_f32 v[108:109], v[100:101], v[108:109]
	v_pk_add_f32 v[100:101], v[98:99], v[106:107]
	v_cvt_pk_bf16_f32 v98, v102, v103
	v_cvt_pk_bf16_f32 v99, v104, v105
	v_cvt_pk_bf16_f32 v100, v100, v101
	v_cvt_pk_bf16_f32 v101, v108, v109
	v_lshl_add_u64 v[102:103], s[6:7], 0, v[116:117]
	global_store_dwordx4 v[102:103], v[98:101], off
	v_lshlrev_b32_e32 v102, 16, v98
	v_lshlrev_b32_e32 v103, 16, v99
	v_and_b32_e32 v98, 0xffff0000, v98
	v_and_b32_e32 v99, 0xffff0000, v99
	v_mul_f32_e32 v98, v98, v98
	v_mul_f32_e32 v99, v99, v99
	v_lshlrev_b32_e32 v104, 16, v100
	v_and_b32_e32 v100, 0xffff0000, v100
	v_fmac_f32_e32 v98, v102, v102
	v_fmac_f32_e32 v99, v103, v103
	v_add_f32_e32 v98, v98, v99
	v_mul_f32_e32 v99, v100, v100
	v_lshlrev_b32_e32 v105, 16, v101
	v_and_b32_e32 v101, 0xffff0000, v101
	v_fmac_f32_e32 v99, v104, v104
	v_add_f32_e32 v98, v99, v98
	v_mul_f32_e32 v99, v101, v101
	v_fmac_f32_e32 v99, v105, v105
	v_add_f32_e32 v98, v99, v98
	v_add_f32_e32 v98, v112, v98
	ds_bpermute_b32 v99, v164, v98
	s_waitcnt lgkmcnt(0)
	v_add_f32_e32 v98, v98, v99
	ds_bpermute_b32 v99, v165, v98
	s_and_saveexec_b64 s[18:19], s[40:41]
	s_cbranch_execz .LBB0_43
	v_lshlrev_b64 v[100:101], 7, v[114:115]
	v_lshl_add_u64 v[100:101], s[10:11], 0, v[100:101]
	v_lshl_add_u64 v[100:101], s[58:59], 2, v[100:101]
	s_lshl_b32 s54, s0, 2
	v_lshl_add_u64 v[100:101], v[100:101], 0, s[54:55]
	s_waitcnt lgkmcnt(0)
	v_add_f32_e32 v98, v98, v99
	global_store_dword v[100:101], v98, off
.LBB0_43:
	s_or_b64 exec, exec, s[18:19]
	v_or_b32_e32 v98, 32, v158
	s_waitcnt lgkmcnt(0)
	v_ashrrev_i32_e32 v99, 31, v98
	v_lshlrev_b64 v[100:101], 11, v[98:99]
	v_lshl_add_u64 v[100:101], v[100:101], 0, v[156:157]
	v_lshlrev_b64 v[100:101], 1, v[100:101]
	v_lshl_add_u64 v[102:103], s[70:71], 0, v[100:101]
	s_waitcnt vmcnt(12)
	v_mov_b32_e32 v102, v212
	v_mov_b32_e32 v103, v213
	v_mov_b32_e32 v104, v214
	v_mov_b32_e32 v105, v215
	v_lshlrev_b32_e32 v106, 16, v102
	v_and_b32_e32 v107, 0xffff0000, v102
	v_lshlrev_b32_e32 v102, 16, v103
	v_and_b32_e32 v103, 0xffff0000, v103
	v_pk_add_f32 v[96:97], v[96:97], v[102:103]
	v_lshlrev_b32_e32 v102, 16, v104
	v_and_b32_e32 v103, 0xffff0000, v104
	v_lshlrev_b32_e32 v104, 16, v105
	v_and_b32_e32 v105, 0xffff0000, v105
	v_pk_add_f32 v[94:95], v[94:95], v[106:107]
	v_pk_add_f32 v[104:105], v[92:93], v[104:105]
	v_pk_add_f32 v[92:93], v[90:91], v[102:103]
	v_cvt_pk_bf16_f32 v90, v94, v95
	v_cvt_pk_bf16_f32 v91, v96, v97
	v_cvt_pk_bf16_f32 v92, v92, v93
	v_cvt_pk_bf16_f32 v93, v104, v105
	v_lshl_add_u64 v[94:95], s[6:7], 0, v[100:101]
	global_store_dwordx4 v[94:95], v[90:93], off
	v_lshlrev_b32_e32 v94, 16, v90
	v_lshlrev_b32_e32 v95, 16, v91
	v_and_b32_e32 v90, 0xffff0000, v90
	v_and_b32_e32 v91, 0xffff0000, v91
	v_mul_f32_e32 v90, v90, v90
	v_mul_f32_e32 v91, v91, v91
	v_lshlrev_b32_e32 v96, 16, v92
	v_and_b32_e32 v92, 0xffff0000, v92
	v_fmac_f32_e32 v90, v94, v94
	v_fmac_f32_e32 v91, v95, v95
	v_add_f32_e32 v90, v90, v91
	v_mul_f32_e32 v91, v92, v92
	v_lshlrev_b32_e32 v97, 16, v93
	v_and_b32_e32 v93, 0xffff0000, v93
	v_fmac_f32_e32 v91, v96, v96
	v_add_f32_e32 v90, v91, v90
	v_mul_f32_e32 v91, v93, v93
	v_fmac_f32_e32 v91, v97, v97
	v_or_b32_e32 v100, 0x100, v100
	v_add_f32_e32 v96, v91, v90
	v_lshl_add_u64 v[90:91], s[70:71], 0, v[100:101]
	s_waitcnt vmcnt(14)
; __device__ __forceinline__ unsigned cvt_pk_bf16(float lo, float hi) { const f32x2c_t v = {lo, hi}; const bf16x2c_t b = __builtin_convertvector(v, bf16x2c_t); return __builtin_bit_cast(unsigned, b); }
; __device__ __forceinline__ float bf_lo(unsigned w) { return __uint_as_float(w << 16); }
; __device__ __forceinline__ float bf_hi(unsigned w) { return __uint_as_float(w & 0xffff0000u); }
;     __device__ __forceinline__ void operator()(const f32x4 (&acc)[2][2][4][2], const Unit& u, int wr, int wc, int fr, int fq) const {
;     ...
;             for (int m = 0; m < 4; ++m) { const size_t row = (size_t)(row0 + ai * HALF + m * 16); float ss = 0.f;
; #pragma unroll
;                 for (int bj = 0; bj < 2; ++bj) { const size_t off = row * DM + col0 + bj * HALF;
;                     const u32x4 pw = *(const u32x4*)(XN + off);
;                     f32x4 v0 = acc[ai][bj][m][0] + (f32x4){bf_lo(pw.x), bf_hi(pw.x), bf_lo(pw.y), bf_hi(pw.y)}, v1 = acc[ai][bj][m][1] + (f32x4){bf_lo(pw.z), bf_hi(pw.z), bf_lo(pw.w), bf_hi(pw.w)};
;                     u32x4 w; w.x = cvt_pk_bf16(v0[0], v0[1]); w.y = cvt_pk_bf16(v0[2], v0[3]); w.z = cvt_pk_bf16(v1[0], v1[1]); w.w = cvt_pk_bf16(v1[2], v1[3]);
;                     *(u32x4*)(X2 + off) = w;
;                     v0 = (f32x4){bf_lo(w.x), bf_hi(w.x), bf_lo(w.y), bf_hi(w.y)}; v1 = (f32x4){bf_lo(w.z), bf_hi(w.z), bf_lo(w.w), bf_hi(w.w)};
;                     ss += (v0[0] * v0[0] + v0[1] * v0[1]) + (v0[2] * v0[2] + v0[3] * v0[3]) + (v1[0] * v1[0] + v1[1] * v1[1]) + (v1[2] * v1[2] + v1[3] * v1[3]); }
;                 ss += __shfl_xor(ss, 16); ss += __shfl_xor(ss, 32);
;                 if (fq == 0) SS[row * 32 + u.pn * 4 + wc] = ss; }
	v_mov_b32_e32 v90, v216
	v_mov_b32_e32 v91, v217
	v_mov_b32_e32 v92, v218
	v_mov_b32_e32 v93, v219
	v_lshlrev_b32_e32 v94, 16, v90
	v_and_b32_e32 v95, 0xffff0000, v90
	v_lshlrev_b32_e32 v90, 16, v91
	v_and_b32_e32 v91, 0xffff0000, v91
	v_pk_add_f32 v[88:89], v[88:89], v[90:91]
	v_lshlrev_b32_e32 v90, 16, v92
	v_and_b32_e32 v91, 0xffff0000, v92
	v_lshlrev_b32_e32 v92, 16, v93
	v_and_b32_e32 v93, 0xffff0000, v93
	v_pk_add_f32 v[86:87], v[86:87], v[94:95]
	v_pk_add_f32 v[92:93], v[84:85], v[92:93]
	v_pk_add_f32 v[84:85], v[82:83], v[90:91]
	v_cvt_pk_bf16_f32 v82, v86, v87
	v_cvt_pk_bf16_f32 v83, v88, v89
	v_cvt_pk_bf16_f32 v84, v84, v85
	v_cvt_pk_bf16_f32 v85, v92, v93
	v_lshl_add_u64 v[86:87], s[6:7], 0, v[100:101]
	global_store_dwordx4 v[86:87], v[82:85], off
	v_lshlrev_b32_e32 v86, 16, v82
	v_lshlrev_b32_e32 v87, 16, v83
	v_and_b32_e32 v82, 0xffff0000, v82
	v_and_b32_e32 v83, 0xffff0000, v83
	v_mul_f32_e32 v82, v82, v82
	v_mul_f32_e32 v83, v83, v83
	v_lshlrev_b32_e32 v88, 16, v84
	v_and_b32_e32 v84, 0xffff0000, v84
	v_fmac_f32_e32 v82, v86, v86
	v_fmac_f32_e32 v83, v87, v87
	v_add_f32_e32 v82, v82, v83
	v_mul_f32_e32 v83, v84, v84
	v_lshlrev_b32_e32 v89, 16, v85
	v_and_b32_e32 v85, 0xffff0000, v85
	v_fmac_f32_e32 v83, v88, v88
	v_add_f32_e32 v82, v83, v82
	v_mul_f32_e32 v83, v85, v85
	v_fmac_f32_e32 v83, v89, v89
	v_add_f32_e32 v82, v83, v82
	v_add_f32_e32 v82, v96, v82
	ds_bpermute_b32 v83, v164, v82
	s_waitcnt lgkmcnt(0)
	v_add_f32_e32 v82, v82, v83
	ds_bpermute_b32 v83, v165, v82
	s_and_saveexec_b64 s[18:19], s[40:41]
	s_cbranch_execz .LBB0_45
	v_lshlrev_b64 v[84:85], 7, v[98:99]
	v_lshl_add_u64 v[84:85], s[10:11], 0, v[84:85]
	v_lshl_add_u64 v[84:85], s[58:59], 2, v[84:85]
	s_lshl_b32 s54, s0, 2
	v_lshl_add_u64 v[84:85], v[84:85], 0, s[54:55]
	s_waitcnt lgkmcnt(0)
	v_add_f32_e32 v82, v82, v83
	global_store_dword v[84:85], v82, off
.LBB0_45:
	s_or_b64 exec, exec, s[18:19]
	v_or_b32_e32 v82, 48, v158
	s_waitcnt lgkmcnt(0)
	v_ashrrev_i32_e32 v83, 31, v82
	v_lshlrev_b64 v[84:85], 11, v[82:83]
	v_lshl_add_u64 v[84:85], v[84:85], 0, v[156:157]
	v_lshlrev_b64 v[84:85], 1, v[84:85]
	v_lshl_add_u64 v[86:87], s[70:71], 0, v[84:85]
	s_waitcnt vmcnt(12)
	v_mov_b32_e32 v86, v220
	v_mov_b32_e32 v87, v221
	v_mov_b32_e32 v88, v222
	v_mov_b32_e32 v89, v223
	v_lshlrev_b32_e32 v90, 16, v86
	v_and_b32_e32 v91, 0xffff0000, v86
	v_lshlrev_b32_e32 v86, 16, v87
	v_and_b32_e32 v87, 0xffff0000, v87
	v_pk_add_f32 v[80:81], v[80:81], v[86:87]
	v_lshlrev_b32_e32 v86, 16, v88
	v_and_b32_e32 v87, 0xffff0000, v88
	v_lshlrev_b32_e32 v88, 16, v89
	v_and_b32_e32 v89, 0xffff0000, v89
	v_pk_add_f32 v[78:79], v[78:79], v[90:91]
	v_pk_add_f32 v[88:89], v[76:77], v[88:89]
	v_pk_add_f32 v[76:77], v[74:75], v[86:87]
	v_cvt_pk_bf16_f32 v74, v78, v79
	v_cvt_pk_bf16_f32 v75, v80, v81
	v_cvt_pk_bf16_f32 v76, v76, v77
	v_cvt_pk_bf16_f32 v77, v88, v89
	v_lshl_add_u64 v[78:79], s[6:7], 0, v[84:85]
	global_store_dwordx4 v[78:79], v[74:77], off
	v_lshlrev_b32_e32 v78, 16, v74
	v_lshlrev_b32_e32 v79, 16, v75
	v_and_b32_e32 v74, 0xffff0000, v74
	v_and_b32_e32 v75, 0xffff0000, v75
	v_mul_f32_e32 v74, v74, v74
	v_mul_f32_e32 v75, v75, v75
	v_lshlrev_b32_e32 v80, 16, v76
	v_and_b32_e32 v76, 0xffff0000, v76
	v_fmac_f32_e32 v74, v78, v78
	v_fmac_f32_e32 v75, v79, v79
	v_add_f32_e32 v74, v74, v75
	v_mul_f32_e32 v75, v76, v76
	v_lshlrev_b32_e32 v81, 16, v77
	v_and_b32_e32 v77, 0xffff0000, v77
	v_fmac_f32_e32 v75, v80, v80
	v_add_f32_e32 v74, v75, v74
	v_mul_f32_e32 v75, v77, v77
	v_fmac_f32_e32 v75, v81, v81
	v_or_b32_e32 v84, 0x100, v84
	v_add_f32_e32 v80, v75, v74
	v_lshl_add_u64 v[74:75], s[70:71], 0, v[84:85]
	s_waitcnt vmcnt(14)
	v_mov_b32_e32 v74, v224
	v_mov_b32_e32 v75, v225
	v_mov_b32_e32 v76, v226
	v_mov_b32_e32 v77, v227
	v_lshlrev_b32_e32 v78, 16, v74
	v_and_b32_e32 v79, 0xffff0000, v74
	v_lshlrev_b32_e32 v74, 16, v75
	v_and_b32_e32 v75, 0xffff0000, v75
	v_pk_add_f32 v[72:73], v[72:73], v[74:75]
	v_lshlrev_b32_e32 v74, 16, v76
	v_and_b32_e32 v75, 0xffff0000, v76
	v_lshlrev_b32_e32 v76, 16, v77
	v_and_b32_e32 v77, 0xffff0000, v77
	v_pk_add_f32 v[70:71], v[70:71], v[78:79]
	v_pk_add_f32 v[76:77], v[68:69], v[76:77]
	v_pk_add_f32 v[68:69], v[66:67], v[74:75]
	v_cvt_pk_bf16_f32 v66, v70, v71
	v_cvt_pk_bf16_f32 v67, v72, v73
	v_cvt_pk_bf16_f32 v68, v68, v69
	v_cvt_pk_bf16_f32 v69, v76, v77
	v_lshl_add_u64 v[70:71], s[6:7], 0, v[84:85]
	global_store_dwordx4 v[70:71], v[66:69], off
	v_lshlrev_b32_e32 v70, 16, v66
	v_lshlrev_b32_e32 v71, 16, v67
	v_and_b32_e32 v66, 0xffff0000, v66
	v_and_b32_e32 v67, 0xffff0000, v67
	v_mul_f32_e32 v66, v66, v66
	v_mul_f32_e32 v67, v67, v67
	v_lshlrev_b32_e32 v72, 16, v68
	v_and_b32_e32 v68, 0xffff0000, v68
	v_fmac_f32_e32 v66, v70, v70
	v_fmac_f32_e32 v67, v71, v71
	v_add_f32_e32 v66, v66, v67
	v_mul_f32_e32 v67, v68, v68
	v_lshlrev_b32_e32 v73, 16, v69
	v_and_b32_e32 v69, 0xffff0000, v69
	v_fmac_f32_e32 v67, v72, v72
	v_add_f32_e32 v66, v67, v66
	v_mul_f32_e32 v67, v69, v69
	v_fmac_f32_e32 v67, v73, v73
	v_add_f32_e32 v66, v67, v66
	v_add_f32_e32 v66, v80, v66
	ds_bpermute_b32 v67, v164, v66
	s_waitcnt lgkmcnt(0)
	v_add_f32_e32 v66, v66, v67
	ds_bpermute_b32 v67, v165, v66
	s_and_saveexec_b64 s[18:19], s[40:41]
	s_cbranch_execz .LBB0_47
	v_lshlrev_b64 v[68:69], 7, v[82:83]
	v_lshl_add_u64 v[68:69], s[10:11], 0, v[68:69]
	v_lshl_add_u64 v[68:69], s[58:59], 2, v[68:69]
	s_lshl_b32 s54, s0, 2
	v_lshl_add_u64 v[68:69], v[68:69], 0, s[54:55]
	s_waitcnt lgkmcnt(0)
	v_add_f32_e32 v66, v66, v67
	global_store_dword v[68:69], v66, off
; __device__ __forceinline__ unsigned cvt_pk_bf16(float lo, float hi) { const f32x2c_t v = {lo, hi}; const bf16x2c_t b = __builtin_convertvector(v, bf16x2c_t); return __builtin_bit_cast(unsigned, b); }
; __device__ __forceinline__ float bf_lo(unsigned w) { return __uint_as_float(w << 16); }
; __device__ __forceinline__ float bf_hi(unsigned w) { return __uint_as_float(w & 0xffff0000u); }
;     __device__ __forceinline__ void operator()(const f32x4 (&acc)[2][2][4][2], const Unit& u, int wr, int wc, int fr, int fq) const {
;     ...
;             for (int m = 0; m < 4; ++m) { const size_t row = (size_t)(row0 + ai * HALF + m * 16); float ss = 0.f;
; #pragma unroll
;                 for (int bj = 0; bj < 2; ++bj) { const size_t off = row * DM + col0 + bj * HALF;
;                     const u32x4 pw = *(const u32x4*)(XN + off);
;                     f32x4 v0 = acc[ai][bj][m][0] + (f32x4){bf_lo(pw.x), bf_hi(pw.x), bf_lo(pw.y), bf_hi(pw.y)}, v1 = acc[ai][bj][m][1] + (f32x4){bf_lo(pw.z), bf_hi(pw.z), bf_lo(pw.w), bf_hi(pw.w)};
;                     u32x4 w; w.x = cvt_pk_bf16(v0[0], v0[1]); w.y = cvt_pk_bf16(v0[2], v0[3]); w.z = cvt_pk_bf16(v1[0], v1[1]); w.w = cvt_pk_bf16(v1[2], v1[3]);
;                     *(u32x4*)(X2 + off) = w;
;                     v0 = (f32x4){bf_lo(w.x), bf_hi(w.x), bf_lo(w.y), bf_hi(w.y)}; v1 = (f32x4){bf_lo(w.z), bf_hi(w.z), bf_lo(w.w), bf_hi(w.w)};
;                     ss += (v0[0] * v0[0] + v0[1] * v0[1]) + (v0[2] * v0[2] + v0[3] * v0[3]) + (v1[0] * v1[0] + v1[1] * v1[1]) + (v1[2] * v1[2] + v1[3] * v1[3]); }
;                 ss += __shfl_xor(ss, 16); ss += __shfl_xor(ss, 32);
;                 if (fq == 0) SS[row * 32 + u.pn * 4 + wc] = ss; }
.LBB0_47:
	s_or_b64 exec, exec, s[18:19]
	v_add_u32_e32 v66, 0x80, v158
	s_waitcnt lgkmcnt(0)
	v_ashrrev_i32_e32 v67, 31, v66
	v_lshlrev_b64 v[68:69], 11, v[66:67]
	v_lshl_add_u64 v[68:69], v[68:69], 0, v[156:157]
	v_lshlrev_b64 v[68:69], 1, v[68:69]
	v_lshl_add_u64 v[70:71], s[70:71], 0, v[68:69]
	s_waitcnt vmcnt(12)
	v_mov_b32_e32 v70, v228
	v_mov_b32_e32 v71, v229
	v_mov_b32_e32 v72, v230
	v_mov_b32_e32 v73, v231
	v_lshlrev_b32_e32 v74, 16, v70
	v_and_b32_e32 v75, 0xffff0000, v70
	v_lshlrev_b32_e32 v70, 16, v71
	v_and_b32_e32 v71, 0xffff0000, v71
	v_pk_add_f32 v[64:65], v[64:65], v[70:71]
	v_lshlrev_b32_e32 v70, 16, v72
	v_and_b32_e32 v71, 0xffff0000, v72
	v_lshlrev_b32_e32 v72, 16, v73
	v_and_b32_e32 v73, 0xffff0000, v73
	v_pk_add_f32 v[62:63], v[62:63], v[74:75]
	v_pk_add_f32 v[72:73], v[60:61], v[72:73]
	v_pk_add_f32 v[60:61], v[58:59], v[70:71]
	v_cvt_pk_bf16_f32 v58, v62, v63
	v_cvt_pk_bf16_f32 v59, v64, v65
	v_cvt_pk_bf16_f32 v60, v60, v61
	v_cvt_pk_bf16_f32 v61, v72, v73
	v_lshl_add_u64 v[62:63], s[6:7], 0, v[68:69]
	global_store_dwordx4 v[62:63], v[58:61], off
	v_lshlrev_b32_e32 v62, 16, v58
	v_lshlrev_b32_e32 v63, 16, v59
	v_and_b32_e32 v58, 0xffff0000, v58
	v_and_b32_e32 v59, 0xffff0000, v59
	v_mul_f32_e32 v58, v58, v58
	v_mul_f32_e32 v59, v59, v59
	v_lshlrev_b32_e32 v64, 16, v60
	v_and_b32_e32 v60, 0xffff0000, v60
	v_fmac_f32_e32 v58, v62, v62
	v_fmac_f32_e32 v59, v63, v63
	v_add_f32_e32 v58, v58, v59
	v_mul_f32_e32 v59, v60, v60
	v_lshlrev_b32_e32 v65, 16, v61
	v_and_b32_e32 v61, 0xffff0000, v61
	v_fmac_f32_e32 v59, v64, v64
	v_add_f32_e32 v58, v59, v58
	v_mul_f32_e32 v59, v61, v61
	v_fmac_f32_e32 v59, v65, v65
	v_or_b32_e32 v68, 0x100, v68
	v_add_f32_e32 v64, v59, v58
	v_lshl_add_u64 v[58:59], s[70:71], 0, v[68:69]
	s_waitcnt vmcnt(14)
	v_mov_b32_e32 v58, v232
	v_mov_b32_e32 v59, v233
	v_mov_b32_e32 v60, v234
	v_mov_b32_e32 v61, v235
	v_lshlrev_b32_e32 v62, 16, v58
	v_and_b32_e32 v63, 0xffff0000, v58
	v_lshlrev_b32_e32 v58, 16, v59
	v_and_b32_e32 v59, 0xffff0000, v59
	v_pk_add_f32 v[56:57], v[56:57], v[58:59]
	v_lshlrev_b32_e32 v58, 16, v60
	v_and_b32_e32 v59, 0xffff0000, v60
	v_lshlrev_b32_e32 v60, 16, v61
	v_and_b32_e32 v61, 0xffff0000, v61
	v_pk_add_f32 v[54:55], v[54:55], v[62:63]
	v_pk_add_f32 v[60:61], v[52:53], v[60:61]
	v_pk_add_f32 v[52:53], v[50:51], v[58:59]
	v_cvt_pk_bf16_f32 v50, v54, v55
	v_cvt_pk_bf16_f32 v51, v56, v57
	v_cvt_pk_bf16_f32 v52, v52, v53
	v_cvt_pk_bf16_f32 v53, v60, v61
	v_lshl_add_u64 v[54:55], s[6:7], 0, v[68:69]
	global_store_dwordx4 v[54:55], v[50:53], off
	v_lshlrev_b32_e32 v54, 16, v50
	v_lshlrev_b32_e32 v55, 16, v51
	v_and_b32_e32 v50, 0xffff0000, v50
	v_and_b32_e32 v51, 0xffff0000, v51
	v_mul_f32_e32 v50, v50, v50
	v_mul_f32_e32 v51, v51, v51
	v_lshlrev_b32_e32 v56, 16, v52
	v_and_b32_e32 v52, 0xffff0000, v52
	v_fmac_f32_e32 v50, v54, v54
	v_fmac_f32_e32 v51, v55, v55
	v_add_f32_e32 v50, v50, v51
	v_mul_f32_e32 v51, v52, v52
	v_lshlrev_b32_e32 v57, 16, v53
	v_and_b32_e32 v53, 0xffff0000, v53
	v_fmac_f32_e32 v51, v56, v56
	v_add_f32_e32 v50, v51, v50
	v_mul_f32_e32 v51, v53, v53
	v_fmac_f32_e32 v51, v57, v57
	v_add_f32_e32 v50, v51, v50
	v_add_f32_e32 v50, v64, v50
	ds_bpermute_b32 v51, v164, v50
	s_waitcnt lgkmcnt(0)
	v_add_f32_e32 v50, v50, v51
	ds_bpermute_b32 v51, v165, v50
	s_and_saveexec_b64 s[18:19], s[40:41]
	s_cbranch_execz .LBB0_49
	v_lshlrev_b64 v[52:53], 7, v[66:67]
	v_lshl_add_u64 v[52:53], s[10:11], 0, v[52:53]
	v_lshl_add_u64 v[52:53], s[58:59], 2, v[52:53]
	s_lshl_b32 s54, s0, 2
	v_lshl_add_u64 v[52:53], v[52:53], 0, s[54:55]
	s_waitcnt lgkmcnt(0)
	v_add_f32_e32 v50, v50, v51
	global_store_dword v[52:53], v50, off
.LBB0_49:
	s_or_b64 exec, exec, s[18:19]
	v_add_u32_e32 v50, 0x90, v158
	s_waitcnt lgkmcnt(0)
	v_ashrrev_i32_e32 v51, 31, v50
	v_lshlrev_b64 v[52:53], 11, v[50:51]
	v_lshl_add_u64 v[52:53], v[52:53], 0, v[156:157]
	v_lshlrev_b64 v[52:53], 1, v[52:53]
	v_lshl_add_u64 v[54:55], s[70:71], 0, v[52:53]
	s_waitcnt vmcnt(12)
	v_mov_b32_e32 v54, v236
	v_mov_b32_e32 v55, v237
	v_mov_b32_e32 v56, v238
	v_mov_b32_e32 v57, v239
	v_lshlrev_b32_e32 v58, 16, v54
	v_and_b32_e32 v59, 0xffff0000, v54
	v_lshlrev_b32_e32 v54, 16, v55
	v_and_b32_e32 v55, 0xffff0000, v55
	v_pk_add_f32 v[48:49], v[48:49], v[54:55]
	v_lshlrev_b32_e32 v54, 16, v56
	v_and_b32_e32 v55, 0xffff0000, v56
	v_lshlrev_b32_e32 v56, 16, v57
	v_and_b32_e32 v57, 0xffff0000, v57
	v_pk_add_f32 v[46:47], v[46:47], v[58:59]
	v_pk_add_f32 v[56:57], v[44:45], v[56:57]
	v_pk_add_f32 v[44:45], v[42:43], v[54:55]
	v_cvt_pk_bf16_f32 v42, v46, v47
	v_cvt_pk_bf16_f32 v43, v48, v49
	v_cvt_pk_bf16_f32 v44, v44, v45
	v_cvt_pk_bf16_f32 v45, v56, v57
	v_lshl_add_u64 v[46:47], s[6:7], 0, v[52:53]
	global_store_dwordx4 v[46:47], v[42:45], off
	v_lshlrev_b32_e32 v46, 16, v42
	v_lshlrev_b32_e32 v47, 16, v43
	v_and_b32_e32 v42, 0xffff0000, v42
	v_and_b32_e32 v43, 0xffff0000, v43
	v_mul_f32_e32 v42, v42, v42
	v_mul_f32_e32 v43, v43, v43
	v_lshlrev_b32_e32 v48, 16, v44
	v_and_b32_e32 v44, 0xffff0000, v44
	v_fmac_f32_e32 v42, v46, v46
	v_fmac_f32_e32 v43, v47, v47
	v_add_f32_e32 v42, v42, v43
	v_mul_f32_e32 v43, v44, v44
	v_lshlrev_b32_e32 v49, 16, v45
	v_and_b32_e32 v45, 0xffff0000, v45
	v_fmac_f32_e32 v43, v48, v48
	v_add_f32_e32 v42, v43, v42
	v_mul_f32_e32 v43, v45, v45
	v_fmac_f32_e32 v43, v49, v49
	v_or_b32_e32 v52, 0x100, v52
	v_add_f32_e32 v48, v43, v42
	v_lshl_add_u64 v[42:43], s[70:71], 0, v[52:53]
	s_waitcnt vmcnt(14)
	v_mov_b32_e32 v42, v240
	v_mov_b32_e32 v43, v241
	v_mov_b32_e32 v44, v242
	v_mov_b32_e32 v45, v243
	v_lshlrev_b32_e32 v46, 16, v42
	v_and_b32_e32 v47, 0xffff0000, v42
	v_lshlrev_b32_e32 v42, 16, v43
	v_and_b32_e32 v43, 0xffff0000, v43
	v_pk_add_f32 v[40:41], v[40:41], v[42:43]
	v_lshlrev_b32_e32 v42, 16, v44
	v_and_b32_e32 v43, 0xffff0000, v44
	v_lshlrev_b32_e32 v44, 16, v45
	v_and_b32_e32 v45, 0xffff0000, v45
	v_pk_add_f32 v[38:39], v[38:39], v[46:47]
	v_pk_add_f32 v[44:45], v[36:37], v[44:45]
	v_pk_add_f32 v[36:37], v[34:35], v[42:43]
	v_cvt_pk_bf16_f32 v34, v38, v39
	v_cvt_pk_bf16_f32 v35, v40, v41
	v_cvt_pk_bf16_f32 v36, v36, v37
	v_cvt_pk_bf16_f32 v37, v44, v45
	v_lshl_add_u64 v[38:39], s[6:7], 0, v[52:53]
	global_store_dwordx4 v[38:39], v[34:37], off
	v_lshlrev_b32_e32 v38, 16, v34
	v_lshlrev_b32_e32 v39, 16, v35
	v_and_b32_e32 v34, 0xffff0000, v34
	v_and_b32_e32 v35, 0xffff0000, v35
	v_mul_f32_e32 v34, v34, v34
	v_mul_f32_e32 v35, v35, v35
	v_lshlrev_b32_e32 v40, 16, v36
	v_and_b32_e32 v36, 0xffff0000, v36
	v_fmac_f32_e32 v34, v38, v38
	v_fmac_f32_e32 v35, v39, v39
	v_add_f32_e32 v34, v34, v35
	v_mul_f32_e32 v35, v36, v36
	v_lshlrev_b32_e32 v41, 16, v37
	v_and_b32_e32 v37, 0xffff0000, v37
	v_fmac_f32_e32 v35, v40, v40
	v_add_f32_e32 v34, v35, v34
	v_mul_f32_e32 v35, v37, v37
	v_fmac_f32_e32 v35, v41, v41
	v_add_f32_e32 v34, v35, v34
	v_add_f32_e32 v34, v48, v34
	ds_bpermute_b32 v35, v164, v34
	s_waitcnt lgkmcnt(0)
	v_add_f32_e32 v34, v34, v35
	ds_bpermute_b32 v35, v165, v34
	s_and_saveexec_b64 s[18:19], s[40:41]
	s_cbranch_execz .LBB0_51
; __device__ __forceinline__ unsigned cvt_pk_bf16(float lo, float hi) { const f32x2c_t v = {lo, hi}; const bf16x2c_t b = __builtin_convertvector(v, bf16x2c_t); return __builtin_bit_cast(unsigned, b); }
; __device__ __forceinline__ float bf_lo(unsigned w) { return __uint_as_float(w << 16); }
; __device__ __forceinline__ float bf_hi(unsigned w) { return __uint_as_float(w & 0xffff0000u); }
;     __device__ __forceinline__ void operator()(const f32x4 (&acc)[2][2][4][2], const Unit& u, int wr, int wc, int fr, int fq) const {
;     ...
;             for (int m = 0; m < 4; ++m) { const size_t row = (size_t)(row0 + ai * HALF + m * 16); float ss = 0.f;
; #pragma unroll
;                 for (int bj = 0; bj < 2; ++bj) { const size_t off = row * DM + col0 + bj * HALF;
;                     const u32x4 pw = *(const u32x4*)(XN + off);
;                     f32x4 v0 = acc[ai][bj][m][0] + (f32x4){bf_lo(pw.x), bf_hi(pw.x), bf_lo(pw.y), bf_hi(pw.y)}, v1 = acc[ai][bj][m][1] + (f32x4){bf_lo(pw.z), bf_hi(pw.z), bf_lo(pw.w), bf_hi(pw.w)};
;                     u32x4 w; w.x = cvt_pk_bf16(v0[0], v0[1]); w.y = cvt_pk_bf16(v0[2], v0[3]); w.z = cvt_pk_bf16(v1[0], v1[1]); w.w = cvt_pk_bf16(v1[2], v1[3]);
;                     *(u32x4*)(X2 + off) = w;
;                     v0 = (f32x4){bf_lo(w.x), bf_hi(w.x), bf_lo(w.y), bf_hi(w.y)}; v1 = (f32x4){bf_lo(w.z), bf_hi(w.z), bf_lo(w.w), bf_hi(w.w)};
;                     ss += (v0[0] * v0[0] + v0[1] * v0[1]) + (v0[2] * v0[2] + v0[3] * v0[3]) + (v1[0] * v1[0] + v1[1] * v1[1]) + (v1[2] * v1[2] + v1[3] * v1[3]); }
;                 ss += __shfl_xor(ss, 16); ss += __shfl_xor(ss, 32);
;                 if (fq == 0) SS[row * 32 + u.pn * 4 + wc] = ss; }
	v_lshlrev_b64 v[36:37], 7, v[50:51]
	v_lshl_add_u64 v[36:37], s[10:11], 0, v[36:37]
	v_lshl_add_u64 v[36:37], s[58:59], 2, v[36:37]
	s_lshl_b32 s54, s0, 2
	v_lshl_add_u64 v[36:37], v[36:37], 0, s[54:55]
	s_waitcnt lgkmcnt(0)
	v_add_f32_e32 v34, v34, v35
	global_store_dword v[36:37], v34, off
.LBB0_51:
	s_or_b64 exec, exec, s[18:19]
	v_add_u32_e32 v34, 0xa0, v158
	s_waitcnt lgkmcnt(0)
	v_ashrrev_i32_e32 v35, 31, v34
	v_lshlrev_b64 v[36:37], 11, v[34:35]
	v_lshl_add_u64 v[36:37], v[36:37], 0, v[156:157]
	v_lshlrev_b64 v[36:37], 1, v[36:37]
	v_lshl_add_u64 v[38:39], s[70:71], 0, v[36:37]
	s_waitcnt vmcnt(12)
	v_mov_b32_e32 v38, v176
	v_mov_b32_e32 v39, v177
	v_mov_b32_e32 v40, v178
	v_mov_b32_e32 v41, v179
	v_lshlrev_b32_e32 v42, 16, v38
	v_and_b32_e32 v43, 0xffff0000, v38
	v_lshlrev_b32_e32 v38, 16, v39
	v_and_b32_e32 v39, 0xffff0000, v39
	v_pk_add_f32 v[32:33], v[32:33], v[38:39]
	v_lshlrev_b32_e32 v38, 16, v40
	v_and_b32_e32 v39, 0xffff0000, v40
	v_lshlrev_b32_e32 v40, 16, v41
	v_and_b32_e32 v41, 0xffff0000, v41
	v_pk_add_f32 v[30:31], v[30:31], v[42:43]
	v_pk_add_f32 v[40:41], v[28:29], v[40:41]
	v_pk_add_f32 v[28:29], v[26:27], v[38:39]
	v_cvt_pk_bf16_f32 v26, v30, v31
	v_cvt_pk_bf16_f32 v27, v32, v33
	v_cvt_pk_bf16_f32 v28, v28, v29
	v_cvt_pk_bf16_f32 v29, v40, v41
	v_lshl_add_u64 v[30:31], s[6:7], 0, v[36:37]
	global_store_dwordx4 v[30:31], v[26:29], off
	v_lshlrev_b32_e32 v30, 16, v26
	v_lshlrev_b32_e32 v31, 16, v27
	v_and_b32_e32 v26, 0xffff0000, v26
	v_and_b32_e32 v27, 0xffff0000, v27
	v_mul_f32_e32 v26, v26, v26
	v_mul_f32_e32 v27, v27, v27
	v_lshlrev_b32_e32 v32, 16, v28
	v_and_b32_e32 v28, 0xffff0000, v28
	v_fmac_f32_e32 v26, v30, v30
	v_fmac_f32_e32 v27, v31, v31
	v_add_f32_e32 v26, v26, v27
	v_mul_f32_e32 v27, v28, v28
	v_lshlrev_b32_e32 v33, 16, v29
	v_and_b32_e32 v29, 0xffff0000, v29
	v_fmac_f32_e32 v27, v32, v32
	v_add_f32_e32 v26, v27, v26
	v_mul_f32_e32 v27, v29, v29
	v_fmac_f32_e32 v27, v33, v33
	v_or_b32_e32 v36, 0x100, v36
	v_add_f32_e32 v32, v27, v26
	v_lshl_add_u64 v[26:27], s[70:71], 0, v[36:37]
	s_waitcnt vmcnt(14)
	v_mov_b32_e32 v26, v180
	v_mov_b32_e32 v27, v181
	v_mov_b32_e32 v28, v182
	v_mov_b32_e32 v29, v183
	v_lshlrev_b32_e32 v30, 16, v26
	v_and_b32_e32 v31, 0xffff0000, v26
	v_lshlrev_b32_e32 v26, 16, v27
	v_and_b32_e32 v27, 0xffff0000, v27
	v_pk_add_f32 v[24:25], v[24:25], v[26:27]
	v_lshlrev_b32_e32 v26, 16, v28
	v_and_b32_e32 v27, 0xffff0000, v28
	v_lshlrev_b32_e32 v28, 16, v29
	v_and_b32_e32 v29, 0xffff0000, v29
	v_pk_add_f32 v[22:23], v[22:23], v[30:31]
	v_pk_add_f32 v[28:29], v[20:21], v[28:29]
	v_pk_add_f32 v[20:21], v[18:19], v[26:27]
	v_cvt_pk_bf16_f32 v18, v22, v23
	v_cvt_pk_bf16_f32 v19, v24, v25
	v_cvt_pk_bf16_f32 v20, v20, v21
	v_cvt_pk_bf16_f32 v21, v28, v29
	v_lshl_add_u64 v[22:23], s[6:7], 0, v[36:37]
	global_store_dwordx4 v[22:23], v[18:21], off
	v_lshlrev_b32_e32 v22, 16, v18
	v_lshlrev_b32_e32 v23, 16, v19
	v_and_b32_e32 v18, 0xffff0000, v18
	v_and_b32_e32 v19, 0xffff0000, v19
	v_mul_f32_e32 v18, v18, v18
	v_mul_f32_e32 v19, v19, v19
	v_lshlrev_b32_e32 v24, 16, v20
	v_and_b32_e32 v20, 0xffff0000, v20
	v_fmac_f32_e32 v18, v22, v22
	v_fmac_f32_e32 v19, v23, v23
	v_add_f32_e32 v18, v18, v19
	v_mul_f32_e32 v19, v20, v20
	v_lshlrev_b32_e32 v25, 16, v21
	v_and_b32_e32 v21, 0xffff0000, v21
	v_fmac_f32_e32 v19, v24, v24
	v_add_f32_e32 v18, v19, v18
	v_mul_f32_e32 v19, v21, v21
	v_fmac_f32_e32 v19, v25, v25
	v_add_f32_e32 v18, v19, v18
	v_add_f32_e32 v18, v32, v18
	ds_bpermute_b32 v19, v164, v18
	s_waitcnt lgkmcnt(0)
	v_add_f32_e32 v18, v18, v19
	ds_bpermute_b32 v19, v165, v18
	s_and_saveexec_b64 s[18:19], s[40:41]
	s_cbranch_execz .LBB0_53
	v_lshlrev_b64 v[20:21], 7, v[34:35]
	v_lshl_add_u64 v[20:21], s[10:11], 0, v[20:21]
	v_lshl_add_u64 v[20:21], s[58:59], 2, v[20:21]
	s_lshl_b32 s54, s0, 2
	v_lshl_add_u64 v[20:21], v[20:21], 0, s[54:55]
	s_waitcnt lgkmcnt(0)
	v_add_f32_e32 v18, v18, v19
	global_store_dword v[20:21], v18, off
